# diff-attn loop rewritten (1 barrier/tile, software-pipelined QK/softmax/PV, scalar f32 ops instead of packed, far-tile bias+max-subtract folded into one fma) + epilogue de-serialization + scan cvt/per
# speedup vs baseline: 1.0100x; 1.0100x over previous
.LBB0_757:
	v_mov_b32_e32 v14, v0
	v_mov_b32_e32 v15, v0
	v_mov_b32_e32 v1, v0
	v_mov_b32_e32 v2, v0
	v_mov_b32_e32 v3, v0
	v_mov_b32_e32 v4, v0
	v_mov_b32_e32 v5, v0
	v_mov_b32_e32 v6, v0
	v_mov_b32_e32 v7, v0
	v_mov_b32_e32 v8, v0
	v_mov_b32_e32 v9, v0
	v_mov_b32_e32 v10, v0
	v_mov_b32_e32 v11, v0
	v_mov_b32_e32 v12, v0
	v_mov_b32_e32 v13, v0
	v_mov_b64_e32 v[30:31], v[14:15]
	v_mov_b64_e32 v[46:47], v[14:15]
	v_mov_b64_e32 v[62:63], v[14:15]
	v_mov_b64_e32 v[78:79], v[14:15]
	s_xor_b64 s[0:1], s[0:1], -1
	v_lshl_add_u64 v[188:189], s[14:15], 1, v[180:181]
	s_mov_b32 s25, 0
	v_mov_b32_e32 v187, 0
	v_mov_b32_e32 v208, 0xff800000
	s_mov_b64 s[4:5], 0
	s_mov_b32 s26, s21
	v_mov_b64_e32 v[28:29], v[12:13]
	v_mov_b64_e32 v[26:27], v[10:11]
	v_mov_b64_e32 v[24:25], v[8:9]
	v_mov_b64_e32 v[22:23], v[6:7]
	v_mov_b64_e32 v[20:21], v[4:5]
	v_mov_b64_e32 v[18:19], v[2:3]
	v_mov_b64_e32 v[16:17], v[0:1]
	v_mov_b64_e32 v[44:45], v[12:13]
	v_mov_b64_e32 v[42:43], v[10:11]
	v_mov_b64_e32 v[40:41], v[8:9]
	v_mov_b64_e32 v[38:39], v[6:7]
	v_mov_b64_e32 v[36:37], v[4:5]
	v_mov_b64_e32 v[34:35], v[2:3]
	v_mov_b64_e32 v[32:33], v[0:1]
	v_mov_b64_e32 v[60:61], v[12:13]
	v_mov_b64_e32 v[58:59], v[10:11]
	v_mov_b64_e32 v[56:57], v[8:9]
	v_mov_b64_e32 v[54:55], v[6:7]
	v_mov_b64_e32 v[52:53], v[4:5]
	v_mov_b64_e32 v[50:51], v[2:3]
	v_mov_b64_e32 v[48:49], v[0:1]
	v_mov_b64_e32 v[76:77], v[12:13]
	v_mov_b64_e32 v[74:75], v[10:11]
	v_mov_b64_e32 v[72:73], v[8:9]
	v_mov_b64_e32 v[70:71], v[6:7]
	v_mov_b64_e32 v[68:69], v[4:5]
	v_mov_b64_e32 v[66:67], v[2:3]
	v_mov_b64_e32 v[64:65], v[0:1]
	s_mov_b32 s27, 0
	s_mov_b32 s100, 0
	v_add_u32_e32 v14, v204, v197
	v_add_u32_e32 v15, v204, v198
	ds_read_b128 v[2:5], v14
	ds_read_b128 v[6:9], v14 offset:4096
	ds_read_b128 v[10:13], v209
	ds_read_b128 v[242:245], v15
	ds_read_b128 v[246:249], v15 offset:4096
	ds_read_b128 v[210:213], v209 offset:1024
	s_waitcnt lgkmcnt(3)
	v_mfma_f32_32x32x16_bf16 v[128:143], v[2:5], v[10:13], 0
	v_mfma_f32_32x32x16_bf16 v[112:127], v[6:9], v[10:13], 0
	s_waitcnt lgkmcnt(0)
	v_mfma_f32_32x32x16_bf16 v[128:143], v[242:245], v[210:213], v[128:143]
	v_mfma_f32_32x32x16_bf16 v[112:127], v[246:249], v[210:213], v[112:127]
	v_add_u32_e32 v14, v204, v199
	v_add_u32_e32 v15, v204, v200
	ds_read_b128 v[2:5], v14
	ds_read_b128 v[6:9], v14 offset:4096
	ds_read_b128 v[10:13], v209 offset:2048
	ds_read_b128 v[242:245], v15
	ds_read_b128 v[246:249], v15 offset:4096
	ds_read_b128 v[210:213], v209 offset:3072
	s_waitcnt lgkmcnt(3)
	v_mfma_f32_32x32x16_bf16 v[128:143], v[2:5], v[10:13], v[128:143]
	v_mfma_f32_32x32x16_bf16 v[112:127], v[6:9], v[10:13], v[112:127]
	s_waitcnt lgkmcnt(0)
	v_mfma_f32_32x32x16_bf16 v[128:143], v[242:245], v[210:213], v[128:143]
	v_mfma_f32_32x32x16_bf16 v[112:127], v[246:249], v[210:213], v[112:127]
	s_add_i32 s14, s26, 0xffffff60
	s_cmp_gt_u32 s14, 0xfffffea0
	s_cbranch_scc1 .Ldq_near_1
	s_sub_i32 s14, s26, 31
	s_cmpk_gt_i32 s14, 0x80
	s_cselect_b32 s14, 0x408, 0
	s_add_i32 s14, s18, s14
	v_mov_b32_e32 v1, s14
	ds_read_b32 v14, v1 offset:29312
	s_nop 7
	s_waitcnt lgkmcnt(0)
	s_nop 3
	v_max3_f32 v225, v128, v129, v130
	v_max3_f32 v225, v225, v131, v132
	v_max3_f32 v225, v225, v133, v134
	v_max3_f32 v225, v225, v135, v136
	v_max3_f32 v225, v225, v137, v138
	v_max3_f32 v225, v225, v139, v140
	v_max3_f32 v225, v225, v141, v142
	v_max3_f32 v225, v225, v143, v112
	v_max3_f32 v225, v225, v113, v114
	v_max3_f32 v225, v225, v115, v116
	v_max3_f32 v225, v225, v117, v118
	v_max3_f32 v225, v225, v119, v120
	v_max3_f32 v225, v225, v121, v122
	v_max3_f32 v225, v225, v123, v124
	v_max3_f32 v225, v225, v125, v126
	v_max_f32_e32 v225, v225, v127
	v_fma_f32 v225, v225, s2, v14
	v_mov_b32_e32 v2, v225
	v_mov_b32_e32 v3, v225
	s_nop 1
	v_permlane32_swap_b32 v2, v3
	s_nop 1
	s_nop 0
	v_max3_f32 v225, v225, v2, v3
	v_add_f32_e32 v2, 0x41000000, v208
	v_cmp_gt_f32_e32 vcc, v225, v2
	s_cbranch_vccz .Ldq_norescale_3
	v_max_f32_e32 v2, v225, v225
	v_max_f32_e32 v3, v208, v208
	v_max_f32_e32 v2, v3, v2
	v_sub_f32_e32 v3, v208, v2
	v_exp_f32_e32 v3, v3
	v_mov_b32_e32 v208, v2
	s_nop 0
	v_mul_f32_e32 v187, v187, v3
	v_mov_b32_e32 v214, v3
	s_mov_b32 s100, 1
.Ldq_norescale_3:
	v_sub_f32_e32 v14, v14, v208
	v_fma_f32 v128, v128, s2, v14
	v_fma_f32 v129, v129, s2, v14
	v_exp_f32_e32 v128, v128
	v_exp_f32_e32 v129, v129
	v_fma_f32 v130, v130, s2, v14
	v_fma_f32 v131, v131, s2, v14
	v_exp_f32_e32 v130, v130
	v_exp_f32_e32 v131, v131
	v_fma_f32 v132, v132, s2, v14
	v_fma_f32 v133, v133, s2, v14
	v_exp_f32_e32 v132, v132
	v_exp_f32_e32 v133, v133
	v_fma_f32 v134, v134, s2, v14
	v_fma_f32 v135, v135, s2, v14
	v_exp_f32_e32 v134, v134
	v_exp_f32_e32 v135, v135
	v_fma_f32 v136, v136, s2, v14
	v_fma_f32 v137, v137, s2, v14
	v_exp_f32_e32 v136, v136
	v_exp_f32_e32 v137, v137
	v_fma_f32 v138, v138, s2, v14
	v_fma_f32 v139, v139, s2, v14
	v_exp_f32_e32 v138, v138
	v_exp_f32_e32 v139, v139
	v_fma_f32 v140, v140, s2, v14
	v_fma_f32 v141, v141, s2, v14
	v_exp_f32_e32 v140, v140
	v_exp_f32_e32 v141, v141
	v_fma_f32 v142, v142, s2, v14
	v_fma_f32 v143, v143, s2, v14
	v_exp_f32_e32 v142, v142
	v_exp_f32_e32 v143, v143
	v_fma_f32 v112, v112, s2, v14
	v_fma_f32 v113, v113, s2, v14
	v_exp_f32_e32 v112, v112
	v_exp_f32_e32 v113, v113
	v_fma_f32 v114, v114, s2, v14
	v_fma_f32 v115, v115, s2, v14
	v_exp_f32_e32 v114, v114
	v_exp_f32_e32 v115, v115
	v_fma_f32 v116, v116, s2, v14
	v_fma_f32 v117, v117, s2, v14
	v_exp_f32_e32 v116, v116
	v_exp_f32_e32 v117, v117
	v_fma_f32 v118, v118, s2, v14
	v_fma_f32 v119, v119, s2, v14
	v_exp_f32_e32 v118, v118
	v_exp_f32_e32 v119, v119
	v_fma_f32 v120, v120, s2, v14
	v_fma_f32 v121, v121, s2, v14
	v_exp_f32_e32 v120, v120
	v_exp_f32_e32 v121, v121
	v_fma_f32 v122, v122, s2, v14
	v_fma_f32 v123, v123, s2, v14
	v_exp_f32_e32 v122, v122
	v_exp_f32_e32 v123, v123
	v_fma_f32 v124, v124, s2, v14
	v_fma_f32 v125, v125, s2, v14
	v_exp_f32_e32 v124, v124
	v_exp_f32_e32 v125, v125
	v_fma_f32 v126, v126, s2, v14
	v_fma_f32 v127, v127, s2, v14
	v_exp_f32_e32 v126, v126
	v_exp_f32_e32 v127, v127
	s_branch .Ldq_smdone_2
.Ldq_near_1:
	v_add_u32_e32 v1, s26, v205
	v_lshl_add_u32 v1, v1, 2, s18
	v_add_u32_e32 v1, 0x7280, v1
	s_nop 7
	s_waitcnt lgkmcnt(0)
	ds_read2_b32 v[2:3], v1 offset0:0 offset1:1
	ds_read2_b32 v[4:5], v1 offset0:2 offset1:3
	ds_read2_b32 v[6:7], v1 offset0:8 offset1:9
	ds_read2_b32 v[8:9], v1 offset0:10 offset1:11
	ds_read2_b32 v[10:11], v1 offset0:16 offset1:17
	ds_read2_b32 v[12:13], v1 offset0:18 offset1:19
	ds_read2_b32 v[242:243], v1 offset0:24 offset1:25
	ds_read2_b32 v[244:245], v1 offset0:26 offset1:27
	s_waitcnt lgkmcnt(0)
	v_fma_f32 v128, v128, s2, v2
	v_fma_f32 v129, v129, s2, v3
	v_fma_f32 v130, v130, s2, v4
	v_fma_f32 v131, v131, s2, v5
	v_fma_f32 v132, v132, s2, v6
	v_fma_f32 v133, v133, s2, v7
	v_fma_f32 v134, v134, s2, v8
	v_fma_f32 v135, v135, s2, v9
	v_fma_f32 v136, v136, s2, v10
	v_fma_f32 v137, v137, s2, v11
	v_fma_f32 v138, v138, s2, v12
	v_fma_f32 v139, v139, s2, v13
	v_fma_f32 v140, v140, s2, v242
	v_fma_f32 v141, v141, s2, v243
	v_fma_f32 v142, v142, s2, v244
	v_fma_f32 v143, v143, s2, v245
	ds_read2_b32 v[2:3], v1 offset0:32 offset1:33
	ds_read2_b32 v[4:5], v1 offset0:34 offset1:35
	ds_read2_b32 v[6:7], v1 offset0:40 offset1:41
	ds_read2_b32 v[8:9], v1 offset0:42 offset1:43
	ds_read2_b32 v[10:11], v1 offset0:48 offset1:49
	ds_read2_b32 v[12:13], v1 offset0:50 offset1:51
	ds_read2_b32 v[242:243], v1 offset0:56 offset1:57
	ds_read2_b32 v[244:245], v1 offset0:58 offset1:59
	s_waitcnt lgkmcnt(0)
	v_fma_f32 v112, v112, s2, v2
	v_fma_f32 v113, v113, s2, v3
	v_fma_f32 v114, v114, s2, v4
	v_fma_f32 v115, v115, s2, v5
	v_fma_f32 v116, v116, s2, v6
	v_fma_f32 v117, v117, s2, v7
	v_fma_f32 v118, v118, s2, v8
	v_fma_f32 v119, v119, s2, v9
	v_fma_f32 v120, v120, s2, v10
	v_fma_f32 v121, v121, s2, v11
	v_fma_f32 v122, v122, s2, v12
	v_fma_f32 v123, v123, s2, v13
	v_fma_f32 v124, v124, s2, v242
	v_fma_f32 v125, v125, s2, v243
	v_fma_f32 v126, v126, s2, v244
	v_fma_f32 v127, v127, s2, v245
	v_max3_f32 v225, v128, v129, v130
	v_max3_f32 v225, v225, v131, v132
	v_max3_f32 v225, v225, v133, v134
	v_max3_f32 v225, v225, v135, v136
	v_max3_f32 v225, v225, v137, v138
	v_max3_f32 v225, v225, v139, v140
	v_max3_f32 v225, v225, v141, v142
	v_max3_f32 v225, v225, v143, v112
	v_max3_f32 v225, v225, v113, v114
	v_max3_f32 v225, v225, v115, v116
	v_max3_f32 v225, v225, v117, v118
	v_max3_f32 v225, v225, v119, v120
	v_max3_f32 v225, v225, v121, v122
	v_max3_f32 v225, v225, v123, v124
	v_max3_f32 v225, v225, v125, v126
	v_max_f32_e32 v225, v225, v127
	v_mov_b32_e32 v14, v225
	v_mov_b32_e32 v15, v225
	s_nop 1
	v_permlane32_swap_b32 v14, v15
	s_nop 1
	s_nop 0
	v_max3_f32 v225, v225, v14, v15
	v_add_f32_e32 v14, 0x41000000, v208
	v_cmp_gt_f32_e32 vcc, v225, v14
	s_cbranch_vccz .Ldq_norescale_4
	v_max_f32_e32 v14, v225, v225
	v_max_f32_e32 v15, v208, v208
	v_max_f32_e32 v14, v15, v14
	v_sub_f32_e32 v15, v208, v14
	v_exp_f32_e32 v15, v15
	v_mov_b32_e32 v208, v14
	s_nop 0
	v_mul_f32_e32 v187, v187, v15
	v_mov_b32_e32 v214, v15
	s_mov_b32 s100, 1
.Ldq_norescale_4:
	v_sub_f32_e32 v128, v128, v208
	v_sub_f32_e32 v129, v129, v208
	v_exp_f32_e32 v128, v128
	v_exp_f32_e32 v129, v129
	v_sub_f32_e32 v130, v130, v208
	v_sub_f32_e32 v131, v131, v208
	v_exp_f32_e32 v130, v130
	v_exp_f32_e32 v131, v131
	v_sub_f32_e32 v132, v132, v208
	v_sub_f32_e32 v133, v133, v208
	v_exp_f32_e32 v132, v132
	v_exp_f32_e32 v133, v133
	v_sub_f32_e32 v134, v134, v208
	v_sub_f32_e32 v135, v135, v208
	v_exp_f32_e32 v134, v134
	v_exp_f32_e32 v135, v135
	v_sub_f32_e32 v136, v136, v208
	v_sub_f32_e32 v137, v137, v208
	v_exp_f32_e32 v136, v136
	v_exp_f32_e32 v137, v137
	v_sub_f32_e32 v138, v138, v208
	v_sub_f32_e32 v139, v139, v208
	v_exp_f32_e32 v138, v138
	v_exp_f32_e32 v139, v139
	v_sub_f32_e32 v140, v140, v208
	v_sub_f32_e32 v141, v141, v208
	v_exp_f32_e32 v140, v140
	v_exp_f32_e32 v141, v141
	v_sub_f32_e32 v142, v142, v208
	v_sub_f32_e32 v143, v143, v208
	v_exp_f32_e32 v142, v142
	v_exp_f32_e32 v143, v143
	v_sub_f32_e32 v112, v112, v208
	v_sub_f32_e32 v113, v113, v208
	v_exp_f32_e32 v112, v112
	v_exp_f32_e32 v113, v113
	v_sub_f32_e32 v114, v114, v208
	v_sub_f32_e32 v115, v115, v208
	v_exp_f32_e32 v114, v114
	v_exp_f32_e32 v115, v115
	v_sub_f32_e32 v116, v116, v208
	v_sub_f32_e32 v117, v117, v208
	v_exp_f32_e32 v116, v116
	v_exp_f32_e32 v117, v117
	v_sub_f32_e32 v118, v118, v208
	v_sub_f32_e32 v119, v119, v208
	v_exp_f32_e32 v118, v118
	v_exp_f32_e32 v119, v119
	v_sub_f32_e32 v120, v120, v208
	v_sub_f32_e32 v121, v121, v208
	v_exp_f32_e32 v120, v120
	v_exp_f32_e32 v121, v121
	v_sub_f32_e32 v122, v122, v208
	v_sub_f32_e32 v123, v123, v208
	v_exp_f32_e32 v122, v122
	v_exp_f32_e32 v123, v123
	v_sub_f32_e32 v124, v124, v208
	v_sub_f32_e32 v125, v125, v208
	v_exp_f32_e32 v124, v124
	v_exp_f32_e32 v125, v125
	v_sub_f32_e32 v126, v126, v208
	v_sub_f32_e32 v127, v127, v208
	v_exp_f32_e32 v126, v126
	v_exp_f32_e32 v127, v127
.Ldq_smdone_2:
	s_nop 0
	v_cvt_pk_bf16_f32 v80, v128, v129
	v_cvt_pk_bf16_f32 v81, v130, v131
	v_cvt_pk_bf16_f32 v82, v132, v133
	v_cvt_pk_bf16_f32 v83, v134, v135
	v_cvt_pk_bf16_f32 v84, v136, v137
	v_cvt_pk_bf16_f32 v85, v138, v139
	v_cvt_pk_bf16_f32 v86, v140, v141
	v_cvt_pk_bf16_f32 v87, v142, v143
	v_cvt_pk_bf16_f32 v88, v112, v113
	v_cvt_pk_bf16_f32 v89, v114, v115
	v_cvt_pk_bf16_f32 v90, v116, v117
	v_cvt_pk_bf16_f32 v91, v118, v119
	v_cvt_pk_bf16_f32 v92, v120, v121
	v_cvt_pk_bf16_f32 v93, v122, v123
	v_cvt_pk_bf16_f32 v94, v124, v125
	v_cvt_pk_bf16_f32 v95, v126, v127
	v_add_f32_e32 v112, v112, v114
	v_add_f32_e32 v113, v113, v115
	v_add_f32_e32 v116, v116, v118
	v_add_f32_e32 v117, v117, v119
	v_add_f32_e32 v120, v120, v122
	v_add_f32_e32 v121, v121, v123
	v_add_f32_e32 v124, v124, v126
	v_add_f32_e32 v125, v125, v127
	v_add_f32_e32 v128, v128, v130
	v_add_f32_e32 v129, v129, v131
	v_add_f32_e32 v132, v132, v134
	v_add_f32_e32 v133, v133, v135
	v_add_f32_e32 v136, v136, v138
	v_add_f32_e32 v137, v137, v139
	v_add_f32_e32 v140, v140, v142
	v_add_f32_e32 v141, v141, v143
	v_add_f32_e32 v112, v112, v116
	v_add_f32_e32 v113, v113, v117
	v_add_f32_e32 v120, v120, v124
	v_add_f32_e32 v121, v121, v125
	v_add_f32_e32 v128, v128, v132
	v_add_f32_e32 v129, v129, v133
	v_add_f32_e32 v136, v136, v140
	v_add_f32_e32 v137, v137, v141
	v_add_f32_e32 v112, v112, v120
	v_add_f32_e32 v113, v113, v121
	v_add_f32_e32 v128, v128, v136
	v_add_f32_e32 v129, v129, v137
	v_add_f32_e32 v112, v112, v128
	v_add_f32_e32 v113, v113, v129
	v_add_f32_e32 v112, v112, v113
	v_add_f32_e32 v187, v187, v112
	s_mov_b32 s100, 0
	s_mov_b32 s25, 1
	s_add_i32 s26, s26, 64
.Ldq_top_5:
	v_lshl_add_u32 v1, s25, 13, v204
	v_add_u32_e32 v14, v1, v197
	v_add_u32_e32 v15, v1, v198
	ds_read_b128 v[2:5], v14
	ds_read_b128 v[6:9], v14 offset:4096
	ds_read_b128 v[10:13], v209
	ds_read_b128 v[242:245], v15
	ds_read_b128 v[246:249], v15 offset:4096
	ds_read_b128 v[210:213], v209 offset:1024
	s_bitcmp1_b32 s27, 0
	s_cselect_b32 s14, 0x5000, 0
	v_add_u32_e32 v250, s14, v201
	ds_read_b64_tr_b16 v[96:97], v250 offset:24576
	ds_read_b64_tr_b16 v[100:101], v250 offset:24640
	ds_read_b64_tr_b16 v[104:105], v250 offset:24704
	ds_read_b64_tr_b16 v[108:109], v250 offset:24768
	ds_read_b64_tr_b16 v[98:99], v250 offset:27136
	ds_read_b64_tr_b16 v[102:103], v250 offset:27200
	ds_read_b64_tr_b16 v[106:107], v250 offset:27264
	ds_read_b64_tr_b16 v[110:111], v250 offset:27328
	s_waitcnt lgkmcnt(11)
	v_mfma_f32_32x32x16_bf16 v[128:143], v[2:5], v[10:13], 0
	v_mfma_f32_32x32x16_bf16 v[112:127], v[6:9], v[10:13], 0
	s_waitcnt lgkmcnt(8)
	v_mfma_f32_32x32x16_bf16 v[128:143], v[242:245], v[210:213], v[128:143]
	v_mfma_f32_32x32x16_bf16 v[112:127], v[246:249], v[210:213], v[112:127]
	v_add_u32_e32 v14, v1, v199
	v_add_u32_e32 v15, v1, v200
	ds_read_b128 v[2:5], v14
	ds_read_b128 v[6:9], v14 offset:4096
	ds_read_b128 v[10:13], v209 offset:2048
	ds_read_b128 v[242:245], v15
	ds_read_b128 v[246:249], v15 offset:4096
	ds_read_b128 v[210:213], v209 offset:3072
	s_add_i32 s14, s27, 1
	s_bitcmp1_b32 s14, 0
	s_cselect_b32 s15, 0x5000, 0
	s_add_i32 s14, s25, 1
	s_cmp_lg_u32 s25, 2
	s_cselect_b32 s14, s14, 0
	v_lshl_add_u32 v251, s14, 13, v192
	s_waitcnt vmcnt(2)
	ds_write_b128 v251, v[156:159]
	v_add3_u32 v251, s15, v193, v194
	s_waitcnt vmcnt(1)
	ds_write_b128 v251, v[148:151] offset:24576
	v_add3_u32 v251, s15, v195, v196
	s_waitcnt vmcnt(0)
	ds_write_b128 v251, v[152:155] offset:24576
	s_cmp_gt_u32 s27, 28
	s_cbranch_scc1 .Ldq_skipk_6
	v_lshl_add_u64 v[14:15], v[188:189], 0, s[4:5]
	global_load_dwordx4 v[156:159], v[14:15], off
.Ldq_skipk_6:
	v_lshl_add_u64 v[14:15], v[184:185], 0, s[4:5]
	global_load_dwordx4 v[148:151], v[14:15], off
	v_lshl_add_u64 v[14:15], v[182:183], 0, s[4:5]
	global_load_dwordx4 v[152:155], v[14:15], off
	s_waitcnt lgkmcnt(6)
	v_mfma_f32_32x32x16_bf16 v[128:143], v[2:5], v[10:13], v[128:143]
	v_mfma_f32_32x32x16_bf16 v[112:127], v[6:9], v[10:13], v[112:127]
	s_waitcnt lgkmcnt(3)
	v_mfma_f32_32x32x16_bf16 v[128:143], v[242:245], v[210:213], v[128:143]
	v_mfma_f32_32x32x16_bf16 v[112:127], v[246:249], v[210:213], v[112:127]
	s_add_i32 s14, s26, 0xffffff60
	s_cmp_gt_u32 s14, 0xfffffea0
	s_cbranch_scc1 .Ldq_near_7
	s_sub_i32 s14, s26, 31
	s_cmpk_gt_i32 s14, 0x80
	s_cselect_b32 s14, 0x408, 0
	s_add_i32 s14, s18, s14
	v_mov_b32_e32 v1, s14
	ds_read_b32 v14, v1 offset:29312
	ds_read_b64_tr_b16 v[226:227], v250 offset:29696
	ds_read_b64_tr_b16 v[230:231], v250 offset:29760
	ds_read_b64_tr_b16 v[234:235], v250 offset:29824
	ds_read_b64_tr_b16 v[238:239], v250 offset:29888
	ds_read_b64_tr_b16 v[228:229], v250 offset:32256
	ds_read_b64_tr_b16 v[232:233], v250 offset:32320
	ds_read_b64_tr_b16 v[236:237], v250 offset:32384
	ds_read_b64_tr_b16 v[240:241], v250 offset:32448
	s_waitcnt lgkmcnt(8)
	s_nop 3
	v_mfma_f32_32x32x16_bf16 v[64:79], v[96:99], v[80:83], v[64:79]
	v_max3_f32 v225, v128, v129, v130
	v_max3_f32 v225, v225, v131, v132
	v_mfma_f32_32x32x16_bf16 v[48:63], v[100:103], v[80:83], v[48:63]
	v_max3_f32 v225, v225, v133, v134
	v_max3_f32 v225, v225, v135, v136
	v_mfma_f32_32x32x16_bf16 v[32:47], v[104:107], v[80:83], v[32:47]
	v_max3_f32 v225, v225, v137, v138
	v_max3_f32 v225, v225, v139, v140
	v_mfma_f32_32x32x16_bf16 v[16:31], v[108:111], v[80:83], v[16:31]
	ds_read_b64_tr_b16 v[96:97], v250 offset:34816
	ds_read_b64_tr_b16 v[100:101], v250 offset:34880
	ds_read_b64_tr_b16 v[104:105], v250 offset:34944
	ds_read_b64_tr_b16 v[108:109], v250 offset:35008
	ds_read_b64_tr_b16 v[98:99], v250 offset:37376
	ds_read_b64_tr_b16 v[102:103], v250 offset:37440
	ds_read_b64_tr_b16 v[106:107], v250 offset:37504
	ds_read_b64_tr_b16 v[110:111], v250 offset:37568
	v_max3_f32 v225, v225, v141, v142
	v_max3_f32 v225, v225, v143, v112
	s_waitcnt lgkmcnt(8)
	v_mfma_f32_32x32x16_bf16 v[64:79], v[226:229], v[84:87], v[64:79]
	v_max3_f32 v225, v225, v113, v114
	v_max3_f32 v225, v225, v115, v116
	v_mfma_f32_32x32x16_bf16 v[48:63], v[230:233], v[84:87], v[48:63]
	v_max3_f32 v225, v225, v117, v118
	v_max3_f32 v225, v225, v119, v120
	v_mfma_f32_32x32x16_bf16 v[32:47], v[234:237], v[84:87], v[32:47]
	v_max3_f32 v225, v225, v121, v122
	v_max3_f32 v225, v225, v123, v124
	v_mfma_f32_32x32x16_bf16 v[16:31], v[238:241], v[84:87], v[16:31]
	v_max3_f32 v225, v225, v125, v126
	v_max_f32_e32 v225, v225, v127
	ds_read_b64_tr_b16 v[226:227], v250 offset:39936
	ds_read_b64_tr_b16 v[230:231], v250 offset:40000
	ds_read_b64_tr_b16 v[234:235], v250 offset:40064
	ds_read_b64_tr_b16 v[238:239], v250 offset:40128
	ds_read_b64_tr_b16 v[228:229], v250 offset:42496
	ds_read_b64_tr_b16 v[232:233], v250 offset:42560
	ds_read_b64_tr_b16 v[236:237], v250 offset:42624
	ds_read_b64_tr_b16 v[240:241], v250 offset:42688
	v_fma_f32 v225, v225, s2, v14
	v_mov_b32_e32 v2, v225
	v_mov_b32_e32 v3, v225
	s_nop 1
	v_permlane32_swap_b32 v2, v3
	s_nop 1
	s_nop 0
	v_max3_f32 v225, v225, v2, v3
	v_add_f32_e32 v2, 0x41000000, v208
	v_cmp_gt_f32_e32 vcc, v225, v2
	s_cbranch_vccz .Ldq_norescale_9
	v_max_f32_e32 v2, v225, v225
	v_max_f32_e32 v3, v208, v208
	v_max_f32_e32 v2, v3, v2
	v_sub_f32_e32 v3, v208, v2
	v_exp_f32_e32 v3, v3
	v_mov_b32_e32 v208, v2
	s_nop 0
	v_mul_f32_e32 v187, v187, v3
	v_mov_b32_e32 v214, v3
	s_mov_b32 s100, 1
.Ldq_norescale_9:
	v_sub_f32_e32 v14, v14, v208
	s_waitcnt lgkmcnt(8)
	v_mfma_f32_32x32x16_bf16 v[64:79], v[96:99], v[88:91], v[64:79]
	v_fma_f32 v128, v128, s2, v14
	v_fma_f32 v129, v129, s2, v14
	v_exp_f32_e32 v128, v128
	v_exp_f32_e32 v129, v129
	v_fma_f32 v130, v130, s2, v14
	v_fma_f32 v131, v131, s2, v14
	v_exp_f32_e32 v130, v130
	v_exp_f32_e32 v131, v131
	v_mfma_f32_32x32x16_bf16 v[48:63], v[100:103], v[88:91], v[48:63]
	v_fma_f32 v132, v132, s2, v14
	v_fma_f32 v133, v133, s2, v14
	v_exp_f32_e32 v132, v132
	v_exp_f32_e32 v133, v133
	v_fma_f32 v134, v134, s2, v14
	v_fma_f32 v135, v135, s2, v14
	v_exp_f32_e32 v134, v134
	v_exp_f32_e32 v135, v135
	v_mfma_f32_32x32x16_bf16 v[32:47], v[104:107], v[88:91], v[32:47]
	v_fma_f32 v136, v136, s2, v14
	v_fma_f32 v137, v137, s2, v14
	v_exp_f32_e32 v136, v136
	v_exp_f32_e32 v137, v137
	v_fma_f32 v138, v138, s2, v14
	v_fma_f32 v139, v139, s2, v14
	v_exp_f32_e32 v138, v138
	v_exp_f32_e32 v139, v139
	v_mfma_f32_32x32x16_bf16 v[16:31], v[108:111], v[88:91], v[16:31]
	v_fma_f32 v140, v140, s2, v14
	v_fma_f32 v141, v141, s2, v14
	v_exp_f32_e32 v140, v140
	v_exp_f32_e32 v141, v141
	v_fma_f32 v142, v142, s2, v14
	v_fma_f32 v143, v143, s2, v14
	v_exp_f32_e32 v142, v142
	v_exp_f32_e32 v143, v143
	s_waitcnt lgkmcnt(0)
	v_mfma_f32_32x32x16_bf16 v[64:79], v[226:229], v[92:95], v[64:79]
	v_fma_f32 v112, v112, s2, v14
	v_fma_f32 v113, v113, s2, v14
	v_exp_f32_e32 v112, v112
	v_exp_f32_e32 v113, v113
	v_fma_f32 v114, v114, s2, v14
	v_fma_f32 v115, v115, s2, v14
	v_exp_f32_e32 v114, v114
	v_exp_f32_e32 v115, v115
	v_mfma_f32_32x32x16_bf16 v[48:63], v[230:233], v[92:95], v[48:63]
	v_fma_f32 v116, v116, s2, v14
	v_fma_f32 v117, v117, s2, v14
	v_exp_f32_e32 v116, v116
	v_exp_f32_e32 v117, v117
	v_fma_f32 v118, v118, s2, v14
	v_fma_f32 v119, v119, s2, v14
	v_exp_f32_e32 v118, v118
	v_exp_f32_e32 v119, v119
	v_mfma_f32_32x32x16_bf16 v[32:47], v[234:237], v[92:95], v[32:47]
	v_fma_f32 v120, v120, s2, v14
	v_fma_f32 v121, v121, s2, v14
	v_exp_f32_e32 v120, v120
	v_exp_f32_e32 v121, v121
	v_fma_f32 v122, v122, s2, v14
	v_fma_f32 v123, v123, s2, v14
	v_exp_f32_e32 v122, v122
	v_exp_f32_e32 v123, v123
	v_mfma_f32_32x32x16_bf16 v[16:31], v[238:241], v[92:95], v[16:31]
	v_fma_f32 v124, v124, s2, v14
	v_fma_f32 v125, v125, s2, v14
	v_exp_f32_e32 v124, v124
	v_exp_f32_e32 v125, v125
	v_fma_f32 v126, v126, s2, v14
	v_fma_f32 v127, v127, s2, v14
	v_exp_f32_e32 v126, v126
	v_exp_f32_e32 v127, v127
	s_branch .Ldq_smdone_8
.Ldq_near_7:
	v_add_u32_e32 v1, s26, v205
	v_lshl_add_u32 v1, v1, 2, s18
	v_add_u32_e32 v1, 0x7280, v1
	s_nop 7
	s_waitcnt lgkmcnt(0)
	ds_read2_b32 v[2:3], v1 offset0:0 offset1:1
	ds_read2_b32 v[4:5], v1 offset0:2 offset1:3
	ds_read2_b32 v[6:7], v1 offset0:8 offset1:9
	ds_read2_b32 v[8:9], v1 offset0:10 offset1:11
	ds_read2_b32 v[10:11], v1 offset0:16 offset1:17
	ds_read2_b32 v[12:13], v1 offset0:18 offset1:19
	ds_read2_b32 v[242:243], v1 offset0:24 offset1:25
	ds_read2_b32 v[244:245], v1 offset0:26 offset1:27
	s_waitcnt lgkmcnt(0)
	v_fma_f32 v128, v128, s2, v2
	v_fma_f32 v129, v129, s2, v3
	v_fma_f32 v130, v130, s2, v4
	v_fma_f32 v131, v131, s2, v5
	v_fma_f32 v132, v132, s2, v6
	v_fma_f32 v133, v133, s2, v7
	v_fma_f32 v134, v134, s2, v8
	v_fma_f32 v135, v135, s2, v9
	v_fma_f32 v136, v136, s2, v10
	v_fma_f32 v137, v137, s2, v11
	v_fma_f32 v138, v138, s2, v12
	v_fma_f32 v139, v139, s2, v13
	v_fma_f32 v140, v140, s2, v242
	v_fma_f32 v141, v141, s2, v243
	v_fma_f32 v142, v142, s2, v244
	v_fma_f32 v143, v143, s2, v245
	ds_read2_b32 v[2:3], v1 offset0:32 offset1:33
	ds_read2_b32 v[4:5], v1 offset0:34 offset1:35
	ds_read2_b32 v[6:7], v1 offset0:40 offset1:41
	ds_read2_b32 v[8:9], v1 offset0:42 offset1:43
	ds_read2_b32 v[10:11], v1 offset0:48 offset1:49
	ds_read2_b32 v[12:13], v1 offset0:50 offset1:51
	ds_read2_b32 v[242:243], v1 offset0:56 offset1:57
	ds_read2_b32 v[244:245], v1 offset0:58 offset1:59
	s_waitcnt lgkmcnt(0)
	v_fma_f32 v112, v112, s2, v2
	v_fma_f32 v113, v113, s2, v3
	v_fma_f32 v114, v114, s2, v4
	v_fma_f32 v115, v115, s2, v5
	v_fma_f32 v116, v116, s2, v6
	v_fma_f32 v117, v117, s2, v7
	v_fma_f32 v118, v118, s2, v8
	v_fma_f32 v119, v119, s2, v9
	v_fma_f32 v120, v120, s2, v10
	v_fma_f32 v121, v121, s2, v11
	v_fma_f32 v122, v122, s2, v12
	v_fma_f32 v123, v123, s2, v13
	v_fma_f32 v124, v124, s2, v242
	v_fma_f32 v125, v125, s2, v243
	v_fma_f32 v126, v126, s2, v244
	v_fma_f32 v127, v127, s2, v245
	ds_read_b64_tr_b16 v[226:227], v250 offset:29696
	ds_read_b64_tr_b16 v[230:231], v250 offset:29760
	ds_read_b64_tr_b16 v[234:235], v250 offset:29824
	ds_read_b64_tr_b16 v[238:239], v250 offset:29888
	ds_read_b64_tr_b16 v[228:229], v250 offset:32256
	ds_read_b64_tr_b16 v[232:233], v250 offset:32320
	ds_read_b64_tr_b16 v[236:237], v250 offset:32384
	ds_read_b64_tr_b16 v[240:241], v250 offset:32448
	v_mfma_f32_32x32x16_bf16 v[64:79], v[96:99], v[80:83], v[64:79]
	v_mfma_f32_32x32x16_bf16 v[48:63], v[100:103], v[80:83], v[48:63]
	v_mfma_f32_32x32x16_bf16 v[32:47], v[104:107], v[80:83], v[32:47]
	v_mfma_f32_32x32x16_bf16 v[16:31], v[108:111], v[80:83], v[16:31]
	s_waitcnt lgkmcnt(0)
	ds_read_b64_tr_b16 v[96:97], v250 offset:34816
	ds_read_b64_tr_b16 v[100:101], v250 offset:34880
	ds_read_b64_tr_b16 v[104:105], v250 offset:34944
	ds_read_b64_tr_b16 v[108:109], v250 offset:35008
	ds_read_b64_tr_b16 v[98:99], v250 offset:37376
	ds_read_b64_tr_b16 v[102:103], v250 offset:37440
	ds_read_b64_tr_b16 v[106:107], v250 offset:37504
	ds_read_b64_tr_b16 v[110:111], v250 offset:37568
	s_waitcnt lgkmcnt(8)
	v_mfma_f32_32x32x16_bf16 v[64:79], v[226:229], v[84:87], v[64:79]
	v_max3_f32 v225, v128, v129, v130
	v_max3_f32 v225, v225, v131, v132
	v_max3_f32 v225, v225, v133, v134
	v_max3_f32 v225, v225, v135, v136
	v_mfma_f32_32x32x16_bf16 v[48:63], v[230:233], v[84:87], v[48:63]
	v_max3_f32 v225, v225, v137, v138
	v_max3_f32 v225, v225, v139, v140
	v_max3_f32 v225, v225, v141, v142
	v_max3_f32 v225, v225, v143, v112
	v_mfma_f32_32x32x16_bf16 v[32:47], v[234:237], v[84:87], v[32:47]
	v_max3_f32 v225, v225, v113, v114
	v_max3_f32 v225, v225, v115, v116
	v_max3_f32 v225, v225, v117, v118
	v_max3_f32 v225, v225, v119, v120
	v_mfma_f32_32x32x16_bf16 v[16:31], v[238:241], v[84:87], v[16:31]
	v_max3_f32 v225, v225, v121, v122
	v_max3_f32 v225, v225, v123, v124
	v_max3_f32 v225, v225, v125, v126
	v_max_f32_e32 v225, v225, v127
	ds_read_b64_tr_b16 v[226:227], v250 offset:39936
	ds_read_b64_tr_b16 v[230:231], v250 offset:40000
	ds_read_b64_tr_b16 v[234:235], v250 offset:40064
	ds_read_b64_tr_b16 v[238:239], v250 offset:40128
	ds_read_b64_tr_b16 v[228:229], v250 offset:42496
	ds_read_b64_tr_b16 v[232:233], v250 offset:42560
	ds_read_b64_tr_b16 v[236:237], v250 offset:42624
	ds_read_b64_tr_b16 v[240:241], v250 offset:42688
	v_mov_b32_e32 v14, v225
	v_mov_b32_e32 v15, v225
	s_nop 1
	v_permlane32_swap_b32 v14, v15
	s_nop 1
	s_nop 0
	v_max3_f32 v225, v225, v14, v15
	v_add_f32_e32 v14, 0x41000000, v208
	v_cmp_gt_f32_e32 vcc, v225, v14
	s_cbranch_vccz .Ldq_norescale_10
	v_max_f32_e32 v14, v225, v225
	v_max_f32_e32 v15, v208, v208
	v_max_f32_e32 v14, v15, v14
	v_sub_f32_e32 v15, v208, v14
	v_exp_f32_e32 v15, v15
	v_mov_b32_e32 v208, v14
	s_nop 0
	v_mul_f32_e32 v187, v187, v15
	v_mov_b32_e32 v214, v15
	s_mov_b32 s100, 1
.Ldq_norescale_10:
	s_waitcnt lgkmcnt(8)
	v_mfma_f32_32x32x16_bf16 v[64:79], v[96:99], v[88:91], v[64:79]
	v_sub_f32_e32 v128, v128, v208
	v_sub_f32_e32 v129, v129, v208
	v_exp_f32_e32 v128, v128
	v_exp_f32_e32 v129, v129
	v_sub_f32_e32 v130, v130, v208
	v_sub_f32_e32 v131, v131, v208
	v_exp_f32_e32 v130, v130
	v_exp_f32_e32 v131, v131
	v_mfma_f32_32x32x16_bf16 v[48:63], v[100:103], v[88:91], v[48:63]
	v_sub_f32_e32 v132, v132, v208
	v_sub_f32_e32 v133, v133, v208
	v_exp_f32_e32 v132, v132
	v_exp_f32_e32 v133, v133
	v_sub_f32_e32 v134, v134, v208
	v_sub_f32_e32 v135, v135, v208
	v_exp_f32_e32 v134, v134
	v_exp_f32_e32 v135, v135
	v_mfma_f32_32x32x16_bf16 v[32:47], v[104:107], v[88:91], v[32:47]
	v_sub_f32_e32 v136, v136, v208
	v_sub_f32_e32 v137, v137, v208
	v_exp_f32_e32 v136, v136
	v_exp_f32_e32 v137, v137
	v_sub_f32_e32 v138, v138, v208
	v_sub_f32_e32 v139, v139, v208
	v_exp_f32_e32 v138, v138
	v_exp_f32_e32 v139, v139
	v_mfma_f32_32x32x16_bf16 v[16:31], v[108:111], v[88:91], v[16:31]
	v_sub_f32_e32 v140, v140, v208
	v_sub_f32_e32 v141, v141, v208
	v_exp_f32_e32 v140, v140
	v_exp_f32_e32 v141, v141
	v_sub_f32_e32 v142, v142, v208
	v_sub_f32_e32 v143, v143, v208
	v_exp_f32_e32 v142, v142
	v_exp_f32_e32 v143, v143
	s_waitcnt lgkmcnt(0)
	v_mfma_f32_32x32x16_bf16 v[64:79], v[226:229], v[92:95], v[64:79]
	v_sub_f32_e32 v112, v112, v208
	v_sub_f32_e32 v113, v113, v208
	v_exp_f32_e32 v112, v112
	v_exp_f32_e32 v113, v113
	v_sub_f32_e32 v114, v114, v208
	v_sub_f32_e32 v115, v115, v208
	v_exp_f32_e32 v114, v114
	v_exp_f32_e32 v115, v115
	v_mfma_f32_32x32x16_bf16 v[48:63], v[230:233], v[92:95], v[48:63]
	v_sub_f32_e32 v116, v116, v208
	v_sub_f32_e32 v117, v117, v208
	v_exp_f32_e32 v116, v116
	v_exp_f32_e32 v117, v117
	v_sub_f32_e32 v118, v118, v208
	v_sub_f32_e32 v119, v119, v208
	v_exp_f32_e32 v118, v118
	v_exp_f32_e32 v119, v119
	v_mfma_f32_32x32x16_bf16 v[32:47], v[234:237], v[92:95], v[32:47]
	v_sub_f32_e32 v120, v120, v208
	v_sub_f32_e32 v121, v121, v208
	v_exp_f32_e32 v120, v120
	v_exp_f32_e32 v121, v121
	v_sub_f32_e32 v122, v122, v208
	v_sub_f32_e32 v123, v123, v208
	v_exp_f32_e32 v122, v122
	v_exp_f32_e32 v123, v123
	v_mfma_f32_32x32x16_bf16 v[16:31], v[238:241], v[92:95], v[16:31]
	v_sub_f32_e32 v124, v124, v208
	v_sub_f32_e32 v125, v125, v208
	v_exp_f32_e32 v124, v124
	v_exp_f32_e32 v125, v125
	v_sub_f32_e32 v126, v126, v208
	v_sub_f32_e32 v127, v127, v208
	v_exp_f32_e32 v126, v126
	v_exp_f32_e32 v127, v127
.Ldq_smdone_8:
	s_nop 0
	v_cvt_pk_bf16_f32 v80, v128, v129
	v_cvt_pk_bf16_f32 v81, v130, v131
	v_cvt_pk_bf16_f32 v82, v132, v133
	v_cvt_pk_bf16_f32 v83, v134, v135
	v_cvt_pk_bf16_f32 v84, v136, v137
	v_cvt_pk_bf16_f32 v85, v138, v139
	v_cvt_pk_bf16_f32 v86, v140, v141
	v_cvt_pk_bf16_f32 v87, v142, v143
	v_cvt_pk_bf16_f32 v88, v112, v113
	v_cvt_pk_bf16_f32 v89, v114, v115
	v_cvt_pk_bf16_f32 v90, v116, v117
	v_cvt_pk_bf16_f32 v91, v118, v119
	v_cvt_pk_bf16_f32 v92, v120, v121
	v_cvt_pk_bf16_f32 v93, v122, v123
	v_cvt_pk_bf16_f32 v94, v124, v125
	v_cvt_pk_bf16_f32 v95, v126, v127
	v_add_f32_e32 v112, v112, v114
	v_add_f32_e32 v113, v113, v115
	v_add_f32_e32 v116, v116, v118
	v_add_f32_e32 v117, v117, v119
	v_add_f32_e32 v120, v120, v122
	v_add_f32_e32 v121, v121, v123
	v_add_f32_e32 v124, v124, v126
	v_add_f32_e32 v125, v125, v127
	v_add_f32_e32 v128, v128, v130
	v_add_f32_e32 v129, v129, v131
	v_add_f32_e32 v132, v132, v134
	v_add_f32_e32 v133, v133, v135
	v_add_f32_e32 v136, v136, v138
	v_add_f32_e32 v137, v137, v139
	v_add_f32_e32 v140, v140, v142
	v_add_f32_e32 v141, v141, v143
	v_add_f32_e32 v112, v112, v116
	v_add_f32_e32 v113, v113, v117
	v_add_f32_e32 v120, v120, v124
	v_add_f32_e32 v121, v121, v125
	v_add_f32_e32 v128, v128, v132
	v_add_f32_e32 v129, v129, v133
	v_add_f32_e32 v136, v136, v140
	v_add_f32_e32 v137, v137, v141
	v_add_f32_e32 v112, v112, v120
	v_add_f32_e32 v113, v113, v121
	v_add_f32_e32 v128, v128, v136
	v_add_f32_e32 v129, v129, v137
	v_add_f32_e32 v112, v112, v128
	v_add_f32_e32 v113, v113, v129
	v_add_f32_e32 v112, v112, v113
	v_add_f32_e32 v187, v187, v112
	s_cmp_eq_u32 s100, 0
	s_cbranch_scc1 .Ldq_noapply_11
	s_nop 7
	s_nop 7
	v_pk_mul_f32 v[78:79], v[78:79], v[214:215] op_sel_hi:[1,0]
	v_pk_mul_f32 v[76:77], v[76:77], v[214:215] op_sel_hi:[1,0]
	v_pk_mul_f32 v[74:75], v[74:75], v[214:215] op_sel_hi:[1,0]
	v_pk_mul_f32 v[72:73], v[72:73], v[214:215] op_sel_hi:[1,0]
	v_pk_mul_f32 v[70:71], v[70:71], v[214:215] op_sel_hi:[1,0]
	v_pk_mul_f32 v[68:69], v[68:69], v[214:215] op_sel_hi:[1,0]
	v_pk_mul_f32 v[66:67], v[66:67], v[214:215] op_sel_hi:[1,0]
	v_pk_mul_f32 v[64:65], v[64:65], v[214:215] op_sel_hi:[1,0]
	v_pk_mul_f32 v[62:63], v[62:63], v[214:215] op_sel_hi:[1,0]
	v_pk_mul_f32 v[60:61], v[60:61], v[214:215] op_sel_hi:[1,0]
	v_pk_mul_f32 v[58:59], v[58:59], v[214:215] op_sel_hi:[1,0]
	v_pk_mul_f32 v[56:57], v[56:57], v[214:215] op_sel_hi:[1,0]
	v_pk_mul_f32 v[54:55], v[54:55], v[214:215] op_sel_hi:[1,0]
	v_pk_mul_f32 v[52:53], v[52:53], v[214:215] op_sel_hi:[1,0]
	v_pk_mul_f32 v[50:51], v[50:51], v[214:215] op_sel_hi:[1,0]
	v_pk_mul_f32 v[48:49], v[48:49], v[214:215] op_sel_hi:[1,0]
	v_pk_mul_f32 v[46:47], v[46:47], v[214:215] op_sel_hi:[1,0]
	v_pk_mul_f32 v[44:45], v[44:45], v[214:215] op_sel_hi:[1,0]
	v_pk_mul_f32 v[42:43], v[42:43], v[214:215] op_sel_hi:[1,0]
	v_pk_mul_f32 v[40:41], v[40:41], v[214:215] op_sel_hi:[1,0]
	v_pk_mul_f32 v[38:39], v[38:39], v[214:215] op_sel_hi:[1,0]
	v_pk_mul_f32 v[36:37], v[36:37], v[214:215] op_sel_hi:[1,0]
	v_pk_mul_f32 v[34:35], v[34:35], v[214:215] op_sel_hi:[1,0]
	v_pk_mul_f32 v[32:33], v[32:33], v[214:215] op_sel_hi:[1,0]
	v_pk_mul_f32 v[30:31], v[30:31], v[214:215] op_sel_hi:[1,0]
	v_pk_mul_f32 v[28:29], v[28:29], v[214:215] op_sel_hi:[1,0]
	v_pk_mul_f32 v[26:27], v[26:27], v[214:215] op_sel_hi:[1,0]
	v_pk_mul_f32 v[24:25], v[24:25], v[214:215] op_sel_hi:[1,0]
	v_pk_mul_f32 v[22:23], v[22:23], v[214:215] op_sel_hi:[1,0]
	v_pk_mul_f32 v[20:21], v[20:21], v[214:215] op_sel_hi:[1,0]
	v_pk_mul_f32 v[18:19], v[18:19], v[214:215] op_sel_hi:[1,0]
	v_pk_mul_f32 v[16:17], v[16:17], v[214:215] op_sel_hi:[1,0]
	s_mov_b32 s100, 0
.Ldq_noapply_11:
	s_waitcnt lgkmcnt(0)
	s_barrier
	s_add_i32 s14, s25, 1
	s_cmp_lg_u32 s25, 2
	s_cselect_b32 s25, s14, 0
	s_add_u32 s4, s4, 0x180000
	s_addc_u32 s5, s5, 0
	s_add_i32 s26, s26, 64
	s_add_i32 s27, s27, 1
	s_cmp_lt_u32 s27, 30
	s_cbranch_scc1 .Ldq_top_5
	v_lshl_add_u32 v1, s25, 13, v204
	v_add_u32_e32 v14, v1, v197
	v_add_u32_e32 v15, v1, v198
	ds_read_b128 v[2:5], v14
	ds_read_b128 v[6:9], v14 offset:4096
	ds_read_b128 v[10:13], v209
	ds_read_b128 v[242:245], v15
	ds_read_b128 v[246:249], v15 offset:4096
	ds_read_b128 v[210:213], v209 offset:1024
	s_bitcmp1_b32 s27, 0
	s_cselect_b32 s14, 0x5000, 0
	v_add_u32_e32 v250, s14, v201
	ds_read_b64_tr_b16 v[96:97], v250 offset:24576
	ds_read_b64_tr_b16 v[100:101], v250 offset:24640
	ds_read_b64_tr_b16 v[104:105], v250 offset:24704
	ds_read_b64_tr_b16 v[108:109], v250 offset:24768
	ds_read_b64_tr_b16 v[98:99], v250 offset:27136
	ds_read_b64_tr_b16 v[102:103], v250 offset:27200
	ds_read_b64_tr_b16 v[106:107], v250 offset:27264
	ds_read_b64_tr_b16 v[110:111], v250 offset:27328
	s_waitcnt lgkmcnt(11)
	v_mfma_f32_32x32x16_bf16 v[128:143], v[2:5], v[10:13], 0
	v_mfma_f32_32x32x16_bf16 v[112:127], v[6:9], v[10:13], 0
	s_waitcnt lgkmcnt(8)
	v_mfma_f32_32x32x16_bf16 v[128:143], v[242:245], v[210:213], v[128:143]
	v_mfma_f32_32x32x16_bf16 v[112:127], v[246:249], v[210:213], v[112:127]
	v_add_u32_e32 v14, v1, v199
	v_add_u32_e32 v15, v1, v200
	ds_read_b128 v[2:5], v14
	ds_read_b128 v[6:9], v14 offset:4096
	ds_read_b128 v[10:13], v209 offset:2048
	ds_read_b128 v[242:245], v15
	ds_read_b128 v[246:249], v15 offset:4096
	ds_read_b128 v[210:213], v209 offset:3072
	s_add_i32 s14, s27, 1
	s_bitcmp1_b32 s14, 0
	s_cselect_b32 s15, 0x5000, 0
	v_add3_u32 v251, s15, v193, v194
	s_waitcnt vmcnt(1)
	ds_write_b128 v251, v[148:151] offset:24576
	v_add3_u32 v251, s15, v195, v196
	s_waitcnt vmcnt(0)
	ds_write_b128 v251, v[152:155] offset:24576
	s_waitcnt lgkmcnt(5)
	v_mfma_f32_32x32x16_bf16 v[128:143], v[2:5], v[10:13], v[128:143]
	v_mfma_f32_32x32x16_bf16 v[112:127], v[6:9], v[10:13], v[112:127]
	s_waitcnt lgkmcnt(2)
	v_mfma_f32_32x32x16_bf16 v[128:143], v[242:245], v[210:213], v[128:143]
	v_mfma_f32_32x32x16_bf16 v[112:127], v[246:249], v[210:213], v[112:127]
	s_add_i32 s14, s26, 0xffffff60
	s_cmp_gt_u32 s14, 0xfffffea0
	s_cbranch_scc1 .Ldq_near_12
	s_sub_i32 s14, s26, 31
	s_cmpk_gt_i32 s14, 0x80
	s_cselect_b32 s14, 0x408, 0
	s_add_i32 s14, s18, s14
	v_mov_b32_e32 v1, s14
	ds_read_b32 v14, v1 offset:29312
	ds_read_b64_tr_b16 v[226:227], v250 offset:29696
	ds_read_b64_tr_b16 v[230:231], v250 offset:29760
	ds_read_b64_tr_b16 v[234:235], v250 offset:29824
	ds_read_b64_tr_b16 v[238:239], v250 offset:29888
	ds_read_b64_tr_b16 v[228:229], v250 offset:32256
	ds_read_b64_tr_b16 v[232:233], v250 offset:32320
	ds_read_b64_tr_b16 v[236:237], v250 offset:32384
	ds_read_b64_tr_b16 v[240:241], v250 offset:32448
	s_waitcnt lgkmcnt(8)
	s_nop 3
	v_mfma_f32_32x32x16_bf16 v[64:79], v[96:99], v[80:83], v[64:79]
	v_max3_f32 v225, v128, v129, v130
	v_max3_f32 v225, v225, v131, v132
	v_mfma_f32_32x32x16_bf16 v[48:63], v[100:103], v[80:83], v[48:63]
	v_max3_f32 v225, v225, v133, v134
	v_max3_f32 v225, v225, v135, v136
	v_mfma_f32_32x32x16_bf16 v[32:47], v[104:107], v[80:83], v[32:47]
	v_max3_f32 v225, v225, v137, v138
	v_max3_f32 v225, v225, v139, v140
	v_mfma_f32_32x32x16_bf16 v[16:31], v[108:111], v[80:83], v[16:31]
	ds_read_b64_tr_b16 v[96:97], v250 offset:34816
	ds_read_b64_tr_b16 v[100:101], v250 offset:34880
	ds_read_b64_tr_b16 v[104:105], v250 offset:34944
	ds_read_b64_tr_b16 v[108:109], v250 offset:35008
	ds_read_b64_tr_b16 v[98:99], v250 offset:37376
	ds_read_b64_tr_b16 v[102:103], v250 offset:37440
	ds_read_b64_tr_b16 v[106:107], v250 offset:37504
	ds_read_b64_tr_b16 v[110:111], v250 offset:37568
	v_max3_f32 v225, v225, v141, v142
	v_max3_f32 v225, v225, v143, v112
	s_waitcnt lgkmcnt(8)
	v_mfma_f32_32x32x16_bf16 v[64:79], v[226:229], v[84:87], v[64:79]
	v_max3_f32 v225, v225, v113, v114
	v_max3_f32 v225, v225, v115, v116
	v_mfma_f32_32x32x16_bf16 v[48:63], v[230:233], v[84:87], v[48:63]
	v_max3_f32 v225, v225, v117, v118
	v_max3_f32 v225, v225, v119, v120
	v_mfma_f32_32x32x16_bf16 v[32:47], v[234:237], v[84:87], v[32:47]
	v_max3_f32 v225, v225, v121, v122
	v_max3_f32 v225, v225, v123, v124
	v_mfma_f32_32x32x16_bf16 v[16:31], v[238:241], v[84:87], v[16:31]
	v_max3_f32 v225, v225, v125, v126
	v_max_f32_e32 v225, v225, v127
	ds_read_b64_tr_b16 v[226:227], v250 offset:39936
	ds_read_b64_tr_b16 v[230:231], v250 offset:40000
	ds_read_b64_tr_b16 v[234:235], v250 offset:40064
	ds_read_b64_tr_b16 v[238:239], v250 offset:40128
	ds_read_b64_tr_b16 v[228:229], v250 offset:42496
	ds_read_b64_tr_b16 v[232:233], v250 offset:42560
	ds_read_b64_tr_b16 v[236:237], v250 offset:42624
	ds_read_b64_tr_b16 v[240:241], v250 offset:42688
	v_fma_f32 v225, v225, s2, v14
	v_mov_b32_e32 v2, v225
	v_mov_b32_e32 v3, v225
	s_nop 1
	v_permlane32_swap_b32 v2, v3
	s_nop 1
	s_nop 0
	v_max3_f32 v225, v225, v2, v3
	v_add_f32_e32 v2, 0x41000000, v208
	v_cmp_gt_f32_e32 vcc, v225, v2
	s_cbranch_vccz .Ldq_norescale_14
	v_max_f32_e32 v2, v225, v225
	v_max_f32_e32 v3, v208, v208
	v_max_f32_e32 v2, v3, v2
	v_sub_f32_e32 v3, v208, v2
	v_exp_f32_e32 v3, v3
	v_mov_b32_e32 v208, v2
	s_nop 0
	v_mul_f32_e32 v187, v187, v3
	v_mov_b32_e32 v214, v3
	s_mov_b32 s100, 1

.Ldq_noapply_16:
	s_waitcnt lgkmcnt(0)
	s_barrier
	s_add_i32 s27, s27, 1
	s_bitcmp1_b32 s27, 0
	s_cselect_b32 s14, 0x5000, 0
	v_add_u32_e32 v250, s14, v201
	ds_read_b64_tr_b16 v[96:97], v250 offset:24576
	ds_read_b64_tr_b16 v[100:101], v250 offset:24640
	ds_read_b64_tr_b16 v[104:105], v250 offset:24704
	ds_read_b64_tr_b16 v[108:109], v250 offset:24768
	ds_read_b64_tr_b16 v[98:99], v250 offset:27136
	ds_read_b64_tr_b16 v[102:103], v250 offset:27200
	ds_read_b64_tr_b16 v[106:107], v250 offset:27264
	ds_read_b64_tr_b16 v[110:111], v250 offset:27328
	ds_read_b64_tr_b16 v[226:227], v250 offset:29696
	ds_read_b64_tr_b16 v[230:231], v250 offset:29760
	ds_read_b64_tr_b16 v[234:235], v250 offset:29824
	ds_read_b64_tr_b16 v[238:239], v250 offset:29888
	ds_read_b64_tr_b16 v[228:229], v250 offset:32256
	ds_read_b64_tr_b16 v[232:233], v250 offset:32320
	ds_read_b64_tr_b16 v[236:237], v250 offset:32384
	ds_read_b64_tr_b16 v[240:241], v250 offset:32448
	s_waitcnt lgkmcnt(8)
	v_mfma_f32_32x32x16_bf16 v[64:79], v[96:99], v[80:83], v[64:79]
	v_mfma_f32_32x32x16_bf16 v[48:63], v[100:103], v[80:83], v[48:63]
	v_mfma_f32_32x32x16_bf16 v[32:47], v[104:107], v[80:83], v[32:47]
	v_mfma_f32_32x32x16_bf16 v[16:31], v[108:111], v[80:83], v[16:31]
	ds_read_b64_tr_b16 v[96:97], v250 offset:34816
	ds_read_b64_tr_b16 v[100:101], v250 offset:34880
	ds_read_b64_tr_b16 v[104:105], v250 offset:34944
	ds_read_b64_tr_b16 v[108:109], v250 offset:35008
	ds_read_b64_tr_b16 v[98:99], v250 offset:37376
	ds_read_b64_tr_b16 v[102:103], v250 offset:37440
	ds_read_b64_tr_b16 v[106:107], v250 offset:37504
	ds_read_b64_tr_b16 v[110:111], v250 offset:37568
	s_waitcnt lgkmcnt(8)
	v_mfma_f32_32x32x16_bf16 v[64:79], v[226:229], v[84:87], v[64:79]
	v_mfma_f32_32x32x16_bf16 v[48:63], v[230:233], v[84:87], v[48:63]
	v_mfma_f32_32x32x16_bf16 v[32:47], v[234:237], v[84:87], v[32:47]
	v_mfma_f32_32x32x16_bf16 v[16:31], v[238:241], v[84:87], v[16:31]
	ds_read_b64_tr_b16 v[226:227], v250 offset:39936
	ds_read_b64_tr_b16 v[230:231], v250 offset:40000
	ds_read_b64_tr_b16 v[234:235], v250 offset:40064
	ds_read_b64_tr_b16 v[238:239], v250 offset:40128
	ds_read_b64_tr_b16 v[228:229], v250 offset:42496
	ds_read_b64_tr_b16 v[232:233], v250 offset:42560
	ds_read_b64_tr_b16 v[236:237], v250 offset:42624
	ds_read_b64_tr_b16 v[240:241], v250 offset:42688
	s_waitcnt lgkmcnt(8)
	v_mfma_f32_32x32x16_bf16 v[64:79], v[96:99], v[88:91], v[64:79]
	v_mfma_f32_32x32x16_bf16 v[48:63], v[100:103], v[88:91], v[48:63]
	v_mfma_f32_32x32x16_bf16 v[32:47], v[104:107], v[88:91], v[32:47]
	v_mfma_f32_32x32x16_bf16 v[16:31], v[108:111], v[88:91], v[16:31]
	s_waitcnt lgkmcnt(0)
	v_mfma_f32_32x32x16_bf16 v[64:79], v[226:229], v[92:95], v[64:79]
	v_mfma_f32_32x32x16_bf16 v[48:63], v[230:233], v[92:95], v[48:63]
	v_mfma_f32_32x32x16_bf16 v[32:47], v[234:237], v[92:95], v[32:47]
	v_mfma_f32_32x32x16_bf16 v[16:31], v[238:241], v[92:95], v[16:31]
	s_waitcnt lgkmcnt(0)
	s_barrier
	s_nop 7
	s_nop 7
	v_mov_b32_e32 v1, v187
	v_mov_b32_e32 v2, v0
	s_nop 0
	v_mbcnt_lo_u32_b32 v2, -1, v2
	v_mbcnt_hi_u32_b32 v2, -1, v2
	v_lshlrev_b32_e32 v2, 2, v2
	v_xor_b32_e32 v2, 0x80, v2
	ds_bpermute_b32 v2, v2, v1
	s_waitcnt lgkmcnt(0)
	v_add_f32_e32 v1, v1, v2
	v_div_scale_f32 v2, s[4:5], v1, v1, 1.0
	v_rcp_f32_e32 v3, v2
	s_nop 0
	v_fma_f32 v4, -v2, v3, 1.0
	v_fmac_f32_e32 v3, v4, v3
	v_div_scale_f32 v4, vcc, 1.0, v1, 1.0
	v_mul_f32_e32 v5, v4, v3
	v_fma_f32 v6, -v2, v5, v4
	v_fmac_f32_e32 v5, v6, v3
	v_fma_f32 v2, -v2, v5, v4
	v_div_fmas_f32 v2, v2, v3, v5
	v_div_fixup_f32 v6, v2, v1, 1.0
	v_cndmask_b32_e64 v1, 0, 1, s[0:1]
	v_cmp_ne_u32_e64 s[4:5], 1, v1
	s_andn2_b64 vcc, exec, s[0:1]
	s_mov_b64 s[0:1], -1
	s_cbranch_vccnz .LBB0_784
	s_load_dwordx2 s[100:101], s[56:57], 0x88
	global_load_dwordx4 v[228:231], v[164:165], off
	global_load_dwordx4 v[8:11], v[164:165], off offset:32
	global_load_dwordx4 v[140:143], v[164:165], off offset:64
	global_load_dwordx4 v[232:235], v[164:165], off offset:96
	global_load_dwordx4 v[148:151], v[164:165], off offset:128
	global_load_dwordx4 v[152:155], v[164:165], off offset:160
	global_load_dwordx4 v[156:159], v[164:165], off offset:192
	global_load_dwordx4 v[210:213], v[164:165], off offset:224
	v_mul_f32_e32 v1, v64, v6
	s_mov_b32 s0, 0x800000
	s_lshl_b64 s[14:15], s[8:9], 2
	v_lshlrev_b32_e32 v139, 2, v162
	s_waitcnt vmcnt(7)
	v_fma_f32 v1, -v160, v1, v228
	v_mul_f32_e32 v2, v65, v6
	v_fma_f32 v7, -v160, v2, v229
	v_mul_f32_e32 v3, v66, v6
	v_fma_f32 v86, -v160, v3, v230
	v_mul_f32_e32 v3, v67, v6
	v_fma_f32 v87, -v160, v3, v231
	v_mul_f32_e32 v3, v68, v6
	s_waitcnt vmcnt(6)
	v_fma_f32 v88, -v160, v3, v8
	v_mul_f32_e32 v3, v69, v6
	v_fma_f32 v89, -v160, v3, v9
	v_mul_f32_e32 v3, v70, v6
	v_fma_f32 v90, -v160, v3, v10
	v_mul_f32_e32 v3, v71, v6
	v_fma_f32 v91, -v160, v3, v11
	global_load_dwordx4 v[228:231], v[164:165], off offset:256
	v_mul_f32_e32 v3, v72, v6
	v_mul_f32_e32 v2, v7, v7
	v_fmac_f32_e32 v2, v1, v1
	v_fmac_f32_e32 v2, v86, v86
	v_fmac_f32_e32 v2, v87, v87
	v_fmac_f32_e32 v2, v88, v88
	v_fmac_f32_e32 v2, v89, v89
	v_fmac_f32_e32 v2, v90, v90
	v_fmac_f32_e32 v2, v91, v91
	v_pk_mul_f32 v[4:5], v[22:23], v[6:7] op_sel_hi:[1,0]
	s_waitcnt vmcnt(6)
	v_fma_f32 v95, -v160, v3, v140
	v_mul_f32_e32 v3, v73, v6
	v_fma_f32 v94, -v160, v3, v141
	v_mul_f32_e32 v3, v74, v6
	v_fma_f32 v93, -v160, v3, v142
	v_mul_f32_e32 v3, v75, v6
	v_fma_f32 v92, -v160, v3, v143
	global_load_dwordx4 v[8:11], v[164:165], off offset:288
	v_mul_f32_e32 v3, v76, v6
	v_fmac_f32_e32 v2, v95, v95
	v_fmac_f32_e32 v2, v94, v94
	v_fmac_f32_e32 v2, v93, v93
	v_fmac_f32_e32 v2, v92, v92
	s_waitcnt vmcnt(6)
	v_fma_f32 v99, -v160, v3, v232
	v_mul_f32_e32 v3, v77, v6
	v_fma_f32 v98, -v160, v3, v233
	v_mul_f32_e32 v3, v78, v6
	v_fma_f32 v97, -v160, v3, v234
	v_mul_f32_e32 v3, v79, v6
	v_fma_f32 v96, -v160, v3, v235
	global_load_dwordx4 v[140:143], v[164:165], off offset:320
	v_mul_f32_e32 v3, v48, v6
	v_fmac_f32_e32 v2, v99, v99
	v_fmac_f32_e32 v2, v98, v98
	v_fmac_f32_e32 v2, v97, v97
	v_fmac_f32_e32 v2, v96, v96
	s_waitcnt vmcnt(6)
	v_fma_f32 v103, -v160, v3, v148
	v_mul_f32_e32 v3, v49, v6
	v_fma_f32 v102, -v160, v3, v149
	v_mul_f32_e32 v3, v50, v6
	v_fma_f32 v101, -v160, v3, v150
	v_mul_f32_e32 v3, v51, v6
	v_fma_f32 v100, -v160, v3, v151
	global_load_dwordx4 v[232:235], v[164:165], off offset:352
	v_mul_f32_e32 v3, v52, v6
	v_fmac_f32_e32 v2, v103, v103
	v_fmac_f32_e32 v2, v102, v102
	v_fmac_f32_e32 v2, v101, v101
	v_fmac_f32_e32 v2, v100, v100
	s_waitcnt vmcnt(6)
	v_fma_f32 v107, -v160, v3, v152
	v_mul_f32_e32 v3, v53, v6
	v_fma_f32 v106, -v160, v3, v153
	v_mul_f32_e32 v3, v54, v6
	v_fma_f32 v105, -v160, v3, v154
	v_mul_f32_e32 v3, v55, v6
	v_fma_f32 v104, -v160, v3, v155
	global_load_dwordx4 v[148:151], v[164:165], off offset:384
	v_mul_f32_e32 v3, v56, v6
	v_fmac_f32_e32 v2, v107, v107
	v_fmac_f32_e32 v2, v106, v106
	v_fmac_f32_e32 v2, v105, v105
	v_fmac_f32_e32 v2, v104, v104
	s_waitcnt vmcnt(6)
	v_fma_f32 v111, -v160, v3, v156
	v_mul_f32_e32 v3, v57, v6
	v_fma_f32 v110, -v160, v3, v157
	v_mul_f32_e32 v3, v58, v6
	v_fma_f32 v109, -v160, v3, v158
	v_mul_f32_e32 v3, v59, v6
	v_fma_f32 v108, -v160, v3, v159
	global_load_dwordx4 v[152:155], v[164:165], off offset:416
	v_mul_f32_e32 v3, v60, v6
	v_fmac_f32_e32 v2, v111, v111
	v_fmac_f32_e32 v2, v110, v110
	v_fmac_f32_e32 v2, v109, v109
	v_fmac_f32_e32 v2, v108, v108
	s_waitcnt vmcnt(6)
	v_fma_f32 v115, -v160, v3, v210
	v_mul_f32_e32 v3, v61, v6
	v_fma_f32 v114, -v160, v3, v211
	v_mul_f32_e32 v3, v62, v6
	v_fma_f32 v113, -v160, v3, v212
	v_mul_f32_e32 v3, v63, v6
	v_fma_f32 v112, -v160, v3, v213
	global_load_dwordx4 v[156:159], v[164:165], off offset:448
	v_mul_f32_e32 v3, v32, v6
	v_fmac_f32_e32 v2, v115, v115
	v_fmac_f32_e32 v2, v114, v114
	v_fmac_f32_e32 v2, v113, v113
	v_fmac_f32_e32 v2, v112, v112
	s_waitcnt vmcnt(6)
	v_fma_f32 v119, -v160, v3, v228
	v_mul_f32_e32 v3, v33, v6
	v_fma_f32 v121, -v160, v3, v229
	v_mul_f32_e32 v3, v34, v6
	v_fma_f32 v118, -v160, v3, v230
	v_mul_f32_e32 v3, v35, v6
	v_fma_f32 v116, -v160, v3, v231
	global_load_dwordx4 v[210:213], v[164:165], off offset:480
	v_mul_f32_e32 v3, v36, v6
	v_fmac_f32_e32 v2, v119, v119
	v_fmac_f32_e32 v2, v121, v121
	v_fmac_f32_e32 v2, v118, v118
	v_fmac_f32_e32 v2, v116, v116
	s_waitcnt vmcnt(6)
	v_fma_f32 v123, -v160, v3, v8
	v_mul_f32_e32 v3, v37, v6
	v_fma_f32 v122, -v160, v3, v9
	v_mul_f32_e32 v3, v38, v6
	v_fma_f32 v120, -v160, v3, v10
	v_mul_f32_e32 v3, v39, v6
	v_fma_f32 v117, -v160, v3, v11
	v_mul_f32_e32 v3, v40, v6
	v_fmac_f32_e32 v2, v123, v123
	v_fmac_f32_e32 v2, v122, v122
	v_fmac_f32_e32 v2, v120, v120
	v_fmac_f32_e32 v2, v117, v117
	s_waitcnt vmcnt(5)
	v_fma_f32 v127, -v160, v3, v140
	v_mul_f32_e32 v3, v41, v6
	v_fma_f32 v126, -v160, v3, v141
	v_mul_f32_e32 v3, v42, v6
	v_fma_f32 v125, -v160, v3, v142
	v_mul_f32_e32 v3, v43, v6
	v_fma_f32 v124, -v160, v3, v143
	v_mul_f32_e32 v3, v44, v6
	v_fmac_f32_e32 v2, v127, v127
	v_fmac_f32_e32 v2, v126, v126
	v_fmac_f32_e32 v2, v125, v125
	v_fmac_f32_e32 v2, v124, v124
	s_waitcnt vmcnt(4)
	v_fma_f32 v131, -v160, v3, v232
	v_mul_f32_e32 v3, v45, v6
	v_fma_f32 v130, -v160, v3, v233
	v_mul_f32_e32 v3, v46, v6
	v_fma_f32 v129, -v160, v3, v234
	v_mul_f32_e32 v3, v47, v6
	v_fma_f32 v128, -v160, v3, v235
	v_mul_f32_e32 v3, v16, v6
	v_fmac_f32_e32 v2, v131, v131
	v_fmac_f32_e32 v2, v130, v130
	v_fmac_f32_e32 v2, v129, v129
	v_fmac_f32_e32 v2, v128, v128
	s_waitcnt vmcnt(3)
	v_fma_f32 v135, -v160, v3, v148
	v_mul_f32_e32 v3, v17, v6
	v_fma_f32 v134, -v160, v3, v149
	v_mul_f32_e32 v3, v18, v6
	v_fma_f32 v133, -v160, v3, v150
	v_mul_f32_e32 v3, v19, v6
	v_fma_f32 v132, -v160, v3, v151
	v_fmac_f32_e32 v2, v135, v135
	v_fmac_f32_e32 v2, v134, v134
	v_fmac_f32_e32 v2, v133, v133
	v_mul_f32_e32 v3, v20, v6
	v_fmac_f32_e32 v2, v132, v132
	s_waitcnt vmcnt(2)
	v_fma_f32 v137, -v160, v3, v152
	v_mul_f32_e32 v3, v21, v6
	v_fmac_f32_e32 v2, v137, v137
	v_fma_f32 v136, -v160, v3, v153
	v_pk_fma_f32 v[8:9], v[160:161], v[4:5], v[154:155] neg_lo:[1,0,0] neg_hi:[1,0,0]
	v_fmac_f32_e32 v2, v136, v136
	v_pk_mul_f32 v[4:5], v[8:9], v[8:9]
	v_pk_mul_f32 v[10:11], v[24:25], v[6:7] op_sel_hi:[1,0]
	v_add_f32_e32 v2, v4, v2
	v_add_f32_e32 v14, v5, v2
	s_waitcnt vmcnt(1)
	v_pk_fma_f32 v[12:13], v[160:161], v[10:11], v[156:157] neg_lo:[1,0,0] neg_hi:[1,0,0]
	s_nop 0
	v_pk_mul_f32 v[2:3], v[12:13], v[12:13]
	s_nop 0
	v_add_f32_e32 v2, v2, v14
	v_add_f32_e32 v14, v3, v2
	v_pk_mul_f32 v[2:3], v[26:27], v[6:7] op_sel_hi:[1,0]
	s_nop 0
	v_pk_fma_f32 v[10:11], v[160:161], v[2:3], v[158:159] neg_lo:[1,0,0] neg_hi:[1,0,0]
	s_nop 0
	v_pk_mul_f32 v[2:3], v[10:11], v[10:11]
	s_nop 0
	v_add_f32_e32 v2, v2, v14
	v_add_f32_e32 v82, v3, v2
	v_pk_mul_f32 v[14:15], v[28:29], v[6:7] op_sel_hi:[1,0]
	s_waitcnt vmcnt(0)
	v_pk_fma_f32 v[80:81], v[160:161], v[14:15], v[210:211] neg_lo:[1,0,0] neg_hi:[1,0,0]
	s_nop 0
	v_pk_mul_f32 v[2:3], v[80:81], v[80:81]
	s_nop 0
	v_add_f32_e32 v2, v2, v82
	v_add_f32_e32 v82, v3, v2
	v_pk_mul_f32 v[2:3], v[30:31], v[6:7] op_sel_hi:[1,0]
	s_waitcnt lgkmcnt(0)
	s_add_u32 s100, s100, s14
	s_addc_u32 s101, s101, s15
	global_load_dwordx4 v[16:19], v139, s[100:101]
	global_load_dwordx4 v[20:23], v139, s[100:101] offset:32
	global_load_dwordx4 v[24:27], v139, s[100:101] offset:64
	global_load_dwordx4 v[28:31], v139, s[100:101] offset:96
	global_load_dwordx4 v[32:35], v139, s[100:101] offset:128
	global_load_dwordx4 v[36:39], v139, s[100:101] offset:160
	global_load_dwordx4 v[40:43], v139, s[100:101] offset:192
	global_load_dwordx4 v[44:47], v139, s[100:101] offset:224
	global_load_dwordx4 v[48:51], v139, s[100:101] offset:256
	global_load_dwordx4 v[52:55], v139, s[100:101] offset:288
	global_load_dwordx4 v[56:59], v139, s[100:101] offset:320
	global_load_dwordx4 v[60:63], v139, s[100:101] offset:352
	global_load_dwordx4 v[64:67], v139, s[100:101] offset:384
	global_load_dwordx4 v[68:71], v139, s[100:101] offset:416
	global_load_dwordx4 v[72:75], v139, s[100:101] offset:448
	global_load_dwordx4 v[76:79], v139, s[100:101] offset:480
	s_nop 0
	v_pk_fma_f32 v[14:15], v[160:161], v[2:3], v[212:213] neg_lo:[1,0,0] neg_hi:[1,0,0]
	v_lshlrev_b32_e32 v4, 1, v162
	v_pk_mul_f32 v[2:3], v[14:15], v[14:15]
	v_mov_b32_e32 v5, v0
	v_add_f32_e32 v2, v2, v82
	v_add_f32_e32 v2, v3, v2
	v_mov_b32_e32 v3, v0
	s_nop 0
	v_mbcnt_lo_u32_b32 v3, -1, v3
	v_mbcnt_hi_u32_b32 v3, -1, v3
	v_lshlrev_b32_e32 v3, 2, v3
	v_xor_b32_e32 v3, 0x80, v3
	ds_bpermute_b32 v3, v3, v2
	s_waitcnt lgkmcnt(0)
	v_add_f32_e32 v2, v2, v3
	v_fmamk_f32 v2, v2, 0x3c000000, v217
	v_cmp_gt_f32_e32 vcc, s0, v2
	v_mul_f32_e32 v3, 0x4b800000, v2
	s_mov_b64 s[0:1], s[56:57]
	v_cndmask_b32_e32 v2, v2, v3, vcc
	v_rsq_f32_e32 v2, v2
	s_load_dwordx2 s[0:1], s[0:1], 0xf0
	v_mul_f32_e32 v3, 0x45800000, v2
	v_cndmask_b32_e32 v2, v2, v3, vcc
	v_mul_f32_e32 v138, v163, v2
	s_waitcnt lgkmcnt(0)
	v_lshl_add_u64 v[2:3], s[0:1], 0, v[178:179]
	v_lshl_add_u64 v[2:3], v[2:3], 0, s[36:37]
	v_lshl_add_u64 v[84:85], v[2:3], 0, v[4:5]
	s_mov_b64 s[0:1], 0x6a701000
	v_lshl_add_u64 v[82:83], v[84:85], 0, s[0:1]
	s_mov_b64 s[0:1], s[56:57]
	s_load_dwordx2 s[0:1], s[0:1], 0x88
	v_mul_f32_e32 v1, v1, v138
	s_waitcnt lgkmcnt(0)
	s_add_u32 s0, s0, s14
	s_addc_u32 s1, s1, s15
	s_waitcnt vmcnt(0)
	v_mul_f32_e32 v1, v16, v1
	v_mul_f32_e32 v2, v7, v138
	v_mul_f32_e32 v2, v17, v2
	v_cvt_pk_bf16_f32 v2, v1, v2
	v_mul_f32_e32 v1, v86, v138
	v_mul_f32_e32 v1, v18, v1
	v_mul_f32_e32 v3, v87, v138
	v_add_co_u32_e32 v4, vcc, s42, v84
	v_mul_f32_e32 v3, v19, v3
	s_nop 0
	v_addc_co_u32_e32 v5, vcc, 0, v85, vcc
	v_cvt_pk_bf16_f32 v3, v1, v3
	global_store_dwordx2 v[4:5], v[2:3], off
	v_mul_f32_e32 v1, v88, v138
	v_mul_f32_e32 v1, v20, v1
	v_mul_f32_e32 v2, v89, v138
	v_mul_f32_e32 v2, v21, v2
	v_mul_f32_e32 v3, v91, v138
	v_cvt_pk_bf16_f32 v2, v1, v2
	v_mul_f32_e32 v1, v90, v138
	v_mul_f32_e32 v3, v23, v3
	v_mul_f32_e32 v1, v22, v1
	v_cvt_pk_bf16_f32 v3, v1, v3
	global_store_dwordx2 v[82:83], v[2:3], off offset:16
	v_mul_f32_e32 v1, v95, v138
	v_mul_f32_e32 v1, v24, v1
	v_mul_f32_e32 v2, v94, v138
	v_mul_f32_e32 v2, v25, v2
	v_mul_f32_e32 v3, v92, v138
	v_cvt_pk_bf16_f32 v2, v1, v2
	v_mul_f32_e32 v1, v93, v138
	v_mul_f32_e32 v3, v27, v3
	v_mul_f32_e32 v1, v26, v1
	v_cvt_pk_bf16_f32 v3, v1, v3
	global_store_dwordx2 v[82:83], v[2:3], off offset:32
	v_mul_f32_e32 v1, v99, v138
	v_mul_f32_e32 v1, v28, v1
	v_mul_f32_e32 v2, v98, v138
	v_mul_f32_e32 v2, v29, v2
	v_mul_f32_e32 v3, v96, v138
	v_cvt_pk_bf16_f32 v2, v1, v2
	v_mul_f32_e32 v1, v97, v138
	v_mul_f32_e32 v3, v31, v3
	v_mul_f32_e32 v1, v30, v1
	v_cvt_pk_bf16_f32 v3, v1, v3
	global_store_dwordx2 v[82:83], v[2:3], off offset:48
	v_mul_f32_e32 v1, v103, v138
	v_mul_f32_e32 v1, v32, v1
	v_mul_f32_e32 v2, v102, v138
	v_mul_f32_e32 v2, v33, v2
	v_mul_f32_e32 v3, v100, v138
	v_cvt_pk_bf16_f32 v2, v1, v2
	v_mul_f32_e32 v1, v101, v138
	v_mul_f32_e32 v3, v35, v3
	v_mul_f32_e32 v1, v34, v1
	v_cvt_pk_bf16_f32 v3, v1, v3
	global_store_dwordx2 v[82:83], v[2:3], off offset:64
	v_mul_f32_e32 v1, v107, v138
	v_mul_f32_e32 v1, v36, v1
	v_mul_f32_e32 v2, v106, v138
	v_mul_f32_e32 v2, v37, v2
	v_mul_f32_e32 v3, v104, v138
	v_cvt_pk_bf16_f32 v2, v1, v2
	v_mul_f32_e32 v1, v105, v138
	v_mul_f32_e32 v3, v39, v3
	v_mul_f32_e32 v1, v38, v1
	v_cvt_pk_bf16_f32 v3, v1, v3
	global_store_dwordx2 v[82:83], v[2:3], off offset:80
	v_mul_f32_e32 v1, v111, v138
	v_mul_f32_e32 v1, v40, v1
	v_mul_f32_e32 v2, v110, v138
	v_mul_f32_e32 v2, v41, v2
	v_mul_f32_e32 v3, v108, v138
	v_cvt_pk_bf16_f32 v2, v1, v2
	v_mul_f32_e32 v1, v109, v138
	v_mul_f32_e32 v3, v43, v3
	v_mul_f32_e32 v1, v42, v1
	v_cvt_pk_bf16_f32 v3, v1, v3
	global_store_dwordx2 v[82:83], v[2:3], off offset:96
	v_mul_f32_e32 v1, v115, v138
	v_mul_f32_e32 v1, v44, v1
	v_mul_f32_e32 v2, v114, v138
	v_mul_f32_e32 v2, v45, v2
	v_mul_f32_e32 v3, v112, v138
	v_cvt_pk_bf16_f32 v2, v1, v2
	v_mul_f32_e32 v1, v113, v138
	v_mul_f32_e32 v3, v47, v3
	v_mul_f32_e32 v1, v46, v1
	v_cvt_pk_bf16_f32 v3, v1, v3
	global_store_dwordx2 v[82:83], v[2:3], off offset:112
	v_mul_f32_e32 v1, v119, v138
	v_mul_f32_e32 v1, v48, v1
	v_mul_f32_e32 v2, v121, v138
	v_mul_f32_e32 v2, v49, v2
	v_mul_f32_e32 v3, v116, v138
	v_cvt_pk_bf16_f32 v2, v1, v2
	v_mul_f32_e32 v1, v118, v138
	v_mul_f32_e32 v3, v51, v3
	v_mul_f32_e32 v1, v50, v1
	v_cvt_pk_bf16_f32 v3, v1, v3
	global_store_dwordx2 v[82:83], v[2:3], off offset:128
	v_mul_f32_e32 v1, v123, v138
	v_mul_f32_e32 v1, v52, v1
	v_mul_f32_e32 v2, v122, v138
	v_mul_f32_e32 v2, v53, v2
	v_mul_f32_e32 v3, v117, v138
	v_cvt_pk_bf16_f32 v2, v1, v2
	v_mul_f32_e32 v1, v120, v138
	v_mul_f32_e32 v3, v55, v3
	v_mul_f32_e32 v1, v54, v1
	v_cvt_pk_bf16_f32 v3, v1, v3
	global_store_dwordx2 v[82:83], v[2:3], off offset:144
	v_mul_f32_e32 v1, v127, v138
	v_mul_f32_e32 v1, v56, v1
	v_mul_f32_e32 v2, v126, v138
	v_mul_f32_e32 v2, v57, v2
	v_mul_f32_e32 v3, v124, v138
	v_cvt_pk_bf16_f32 v2, v1, v2
	v_mul_f32_e32 v1, v125, v138
	v_mul_f32_e32 v3, v59, v3
	v_mul_f32_e32 v1, v58, v1
	v_cvt_pk_bf16_f32 v3, v1, v3
	global_store_dwordx2 v[82:83], v[2:3], off offset:160
	v_mul_f32_e32 v1, v131, v138
	v_mul_f32_e32 v1, v60, v1
	v_mul_f32_e32 v2, v130, v138
	v_mul_f32_e32 v2, v61, v2
	v_mul_f32_e32 v3, v128, v138
	v_cvt_pk_bf16_f32 v2, v1, v2
	v_mul_f32_e32 v1, v129, v138
	v_mul_f32_e32 v3, v63, v3
	v_mul_f32_e32 v1, v62, v1
	v_cvt_pk_bf16_f32 v3, v1, v3
	global_store_dwordx2 v[82:83], v[2:3], off offset:176
	v_mul_f32_e32 v1, v135, v138
	v_mul_f32_e32 v1, v64, v1
	v_mul_f32_e32 v2, v134, v138
	v_mul_f32_e32 v2, v65, v2
	v_mul_f32_e32 v3, v132, v138
	v_cvt_pk_bf16_f32 v2, v1, v2
	v_mul_f32_e32 v1, v133, v138
	v_mul_f32_e32 v3, v67, v3
	v_mul_f32_e32 v1, v66, v1
	v_cvt_pk_bf16_f32 v3, v1, v3
	global_store_dwordx2 v[82:83], v[2:3], off offset:192
	v_mul_f32_e32 v1, v137, v138
	v_mul_f32_e32 v1, v1, v68
	v_mul_f32_e32 v2, v136, v138
	v_mul_f32_e32 v2, v2, v69
	v_mul_f32_e32 v3, v9, v138
	v_cvt_pk_bf16_f32 v2, v1, v2
	v_mul_f32_e32 v1, v8, v138
	v_mul_f32_e32 v3, v3, v71
	v_mul_f32_e32 v1, v1, v70
	v_cvt_pk_bf16_f32 v3, v1, v3
	global_store_dwordx2 v[82:83], v[2:3], off offset:208
	v_mul_f32_e32 v1, v12, v138
	v_mul_f32_e32 v1, v1, v72
	v_mul_f32_e32 v2, v13, v138
	v_mul_f32_e32 v2, v2, v73
	v_mul_f32_e32 v3, v11, v138
	v_cvt_pk_bf16_f32 v2, v1, v2
	v_mul_f32_e32 v1, v10, v138
	v_mul_f32_e32 v3, v3, v75
	v_mul_f32_e32 v1, v1, v74
	v_cvt_pk_bf16_f32 v3, v1, v3
	global_store_dwordx2 v[82:83], v[2:3], off offset:224
	v_mul_f32_e32 v1, v80, v138
	v_mul_f32_e32 v1, v1, v76
	v_mul_f32_e32 v2, v81, v138
	v_mul_f32_e32 v2, v2, v77
	v_mul_f32_e32 v3, v15, v138
	v_cvt_pk_bf16_f32 v2, v1, v2
	v_mul_f32_e32 v1, v14, v138
	v_mul_f32_e32 v3, v3, v79
	v_mul_f32_e32 v1, v1, v78
	v_cvt_pk_bf16_f32 v3, v1, v3
	global_store_dwordx2 v[82:83], v[2:3], off offset:240
	s_cbranch_execnz .LBB0_754
	s_branch .LBB0_785
